# HGRN2 mix_a / mix_c items: lb table loaded one item ahead into spare registers; head waits no longer cover the fresh next-item prefetch
# speedup vs baseline: 1.0134x; 1.0125x over previous
.LBB0_443:
	v_mov_b32_e32 v2, v1
	v_mov_b32_e32 v3, v1
	v_mov_b32_e32 v0, v1
	v_mov_b64_e32 v[22:23], v[2:3]
	s_waitcnt vmcnt(15)
	v_mov_b64_e32 v[34:35], v[2:3]
	v_mov_b64_e32 v[38:39], v[2:3]
	v_mov_b64_e32 v[46:47], v[2:3]
	s_waitcnt vmcnt(6)
	v_mov_b64_e32 v[42:43], v[2:3]
	v_mov_b64_e32 v[50:51], v[2:3]
	v_readlane_b32 s2, v238, 11
	s_mov_b32 s77, s3
	s_mov_b32 s79, s97
	v_mov_b64_e32 v[20:21], v[0:1]
	v_mov_b64_e32 v[32:33], v[0:1]
	v_mov_b64_e32 v[36:37], v[0:1]
	v_mov_b64_e32 v[44:45], v[0:1]
	v_mov_b64_e32 v[40:41], v[0:1]
	v_mov_b64_e32 v[48:49], v[0:1]
	s_bfe_u32 s100, s97, 0x20006
	s_lshl_b32 s100, s100, 9
	s_add_u32 s98, s33, s100
	s_addc_u32 s99, s34, 0
	v_and_b32_e32 v239, 15, v204
	v_lshlrev_b32_e32 v239, 5, v239
	global_load_dwordx4 v[240:243], v239, s[98:99]
	global_load_dwordx4 v[244:247], v239, s[98:99] offset:16
	s_waitcnt vmcnt(0)
	s_branch .LBB0_446
.Llbp_a8:
	s_waitcnt vmcnt(8)
	s_branch .LBB0_448

.LBB0_446:
	s_add_i32 s78, s79, s22
	s_cmpk_gt_i32 s78, 0x7ff
	s_cbranch_scc1 .Llbp_a8
	v_mov_b32_e32 v0, v204
	s_ashr_i32 s6, s78, 8
	v_ashrrev_i32_e32 v2, 31, v0
	v_lshrrev_b32_e32 v2, 28, v2
	v_add_u32_e32 v3, v0, v2
	s_ashr_i32 s7, s6, 31
	s_add_i32 s8, s90, s77
	v_ashrrev_i32_e32 v2, 4, v3
	v_and_b32_e32 v3, 0x1ffffff0, v3
	s_lshl_b64 s[6:7], s[6:7], 12
	s_and_b32 s8, s8, 0xfc0
	v_sub_u32_e32 v3, v0, v3
	s_or_b32 s6, s6, s8
	v_lshlrev_b32_e32 v20, 3, v3
	v_ashrrev_i32_e32 v3, 31, v2
	s_add_i32 s8, s89, s2
	v_lshl_add_u64 v[2:3], s[6:7], 0, v[2:3]
	v_mov_b64_e32 v[44:45], s[54:55]
	s_and_b32 s10, s8, 0x180
	v_mad_u64_u32 v[22:23], s[8:9], v2, s46, v[44:45]
	v_mad_i32_i24 v23, v3, s46, v23
	s_lshl_b32 s26, s10, 1
	v_lshl_add_u64 v[2:3], v[22:23], 0, s[26:27]
	v_ashrrev_i32_e32 v21, 31, v20
	v_lshl_add_u64 v[2:3], v[20:21], 1, v[2:3]
	v_add_u32_e32 v21, 0x200, v0
	v_ashrrev_i32_e32 v20, 31, v21
	v_lshrrev_b32_e32 v20, 28, v20
	v_add_u32_e32 v22, v21, v20
	v_ashrrev_i32_e32 v20, 4, v22
	v_and_b32_e32 v22, 0x1ffffff0, v22
	v_sub_u32_e32 v21, v21, v22
	v_lshlrev_b32_e32 v22, 3, v21
	v_ashrrev_i32_e32 v21, 31, v20
	v_lshl_add_u64 v[20:21], s[6:7], 0, v[20:21]
	v_mad_u64_u32 v[32:33], s[8:9], v20, s46, v[44:45]
	v_mad_i32_i24 v33, v21, s46, v33
	v_add_co_u32_e32 v2, vcc, s1, v2
	v_lshl_add_u64 v[20:21], v[32:33], 0, s[26:27]
	v_ashrrev_i32_e32 v23, 31, v22
	v_addc_co_u32_e32 v3, vcc, 0, v3, vcc
	v_lshl_add_u64 v[20:21], v[22:23], 1, v[20:21]
	v_add_co_u32_e32 v32, vcc, s1, v20
	s_nop 1
	v_addc_co_u32_e32 v33, vcc, 0, v21, vcc
	global_load_dwordx4 v[20:23], v[2:3], off offset:1024
	s_nop 0
	global_load_dwordx4 v[32:35], v[32:33], off offset:1024
	v_ashrrev_i32_e32 v2, 4, v0
	v_ashrrev_i32_e32 v3, 31, v2
	v_lshl_add_u64 v[36:37], s[6:7], 0, v[2:3]
	v_add_u32_e32 v2, 32, v2
	v_ashrrev_i32_e32 v3, 31, v2
	v_lshl_add_u64 v[2:3], s[6:7], 0, v[2:3]
	v_mad_u64_u32 v[38:39], s[8:9], v36, s46, v[44:45]
	v_mad_u64_u32 v[44:45], s[6:7], v2, s46, v[44:45]
	v_mad_i32_i24 v39, v37, s46, v39
	v_lshlrev_b32_e32 v0, 4, v0
	v_mad_i32_i24 v45, v3, s46, v45
	v_lshl_add_u64 v[36:37], v[38:39], 0, s[26:27]
	v_and_b32_e32 v0, 0xf0, v0
	v_lshl_add_u64 v[2:3], v[44:45], 0, s[26:27]
	v_lshl_add_u64 v[36:37], v[36:37], 0, v[0:1]
	v_lshl_add_u64 v[2:3], v[2:3], 0, v[0:1]
	v_lshl_add_u64 v[40:41], v[36:37], 0, s[64:65]
	v_lshl_add_u64 v[48:49], v[2:3], 0, s[64:65]
	global_load_dwordx4 v[36:39], v[36:37], off offset:3072
	s_nop 0
	global_load_dwordx4 v[40:43], v[40:41], off offset:1024
	s_nop 0
	global_load_dwordx4 v[44:47], v[2:3], off offset:3072
	s_nop 0
	global_load_dwordx4 v[48:51], v[48:49], off offset:1024
	s_waitcnt vmcnt(14)
.LBB0_448:
	s_bfe_u32 s26, s79, 0x20006
	v_mov_b32_e32 v2, v204
	s_lshl_b32 s6, s26, 9
	v_lshlrev_b32_e32 v0, 3, v2
	v_and_b32_e32 v107, 0x78, v0
	s_add_u32 s6, s33, s6
	s_addc_u32 s7, s34, 0
	v_lshlrev_b32_e32 v60, 2, v107
	v_mov_b32_e32 v56, v240
	v_mov_b32_e32 v57, v241
	v_mov_b32_e32 v58, v242
	v_mov_b32_e32 v59, v243
	v_mov_b32_e32 v52, v244
	v_mov_b32_e32 v53, v245
	v_mov_b32_e32 v54, v246
	v_mov_b32_e32 v55, v247
	s_add_i32 s100, s79, s22
	s_bfe_u32 s100, s100, 0x20006
	s_lshl_b32 s100, s100, 9
	s_add_u32 s98, s33, s100
	s_addc_u32 s99, s34, 0
	global_load_dwordx4 v[240:243], v60, s[98:99]
	global_load_dwordx4 v[244:247], v60, s[98:99] offset:16
	s_nop 0
	v_lshlrev_b32_e32 v3, 16, v16
	v_and_b32_e32 v61, 0xffff0000, v16
	v_mul_f32_e32 v66, 0xbfb8aa3b, v3
	v_mul_f32_e32 v61, 0xbfb8aa3b, v61
	v_exp_f32_e32 v72, v66
	v_exp_f32_e32 v73, v61
	v_lshlrev_b32_e32 v62, 16, v17
	v_and_b32_e32 v63, 0xffff0000, v17
	v_lshlrev_b32_e32 v64, 16, v18
	v_and_b32_e32 v65, 0xffff0000, v18
	v_mul_f32_e32 v62, 0xbfb8aa3b, v62
	v_mul_f32_e32 v63, 0xbfb8aa3b, v63
	v_mul_f32_e32 v64, 0xbfb8aa3b, v64
	v_mul_f32_e32 v65, 0xbfb8aa3b, v65
	v_ashrrev_i32_e32 v3, 31, v2
	v_add_u32_e32 v67, 0x200, v2
	v_exp_f32_e32 v70, v62
	v_lshlrev_b32_e32 v80, 16, v19
	v_and_b32_e32 v81, 0xffff0000, v19
	v_lshlrev_b32_e32 v74, 2, v2
	v_exp_f32_e32 v71, v63
	v_exp_f32_e32 v68, v64
	v_exp_f32_e32 v69, v65
	v_lshrrev_b32_e32 v61, 28, v3
	v_ashrrev_i32_e32 v62, 31, v67
	v_add_f32_e32 v64, 1.0, v72
	v_add_f32_e32 v65, 1.0, v73
	v_ashrrev_i32_e32 v108, 4, v2
	v_and_b32_e32 v63, 0x1fc, v74
	v_add_u32_e32 v61, v2, v61
	v_lshrrev_b32_e32 v62, 28, v62
	v_rcp_f32_e32 v78, v64
	v_rcp_f32_e32 v79, v65
	v_mul_f32_e32 v80, 0xbfb8aa3b, v80
	v_mul_f32_e32 v81, 0xbfb8aa3b, v81
	v_lshlrev_b32_e32 v106, 9, v108
	v_add_u32_e32 v100, 0, v63
	v_add_u32_e32 v102, s92, v63
	v_lshrrev_b32_e32 v63, 4, v61
	v_and_b32_e32 v61, 0xffffff0, v61
	v_add_u32_e32 v62, v67, v62
	v_exp_f32_e32 v80, v80
	v_exp_f32_e32 v81, v81
	v_add3_u32 v104, 0, v106, v60
	v_sub_u32_e32 v60, v2, v61
	v_mul_lo_u32 v61, v63, s76
	v_lshrrev_b32_e32 v63, 4, v62
	v_and_b32_e32 v62, 0xffffff0, v62
	v_add_f32_e32 v66, 1.0, v70
	v_add_u32_e32 v103, s92, v74
	v_add_f32_e32 v74, 1.0, v71
	v_add_f32_e32 v75, 1.0, v68
	v_sub_u32_e32 v62, v67, v62
	v_rcp_f32_e32 v76, v66
	v_add_f32_e32 v82, 1.0, v69
	v_rcp_f32_e32 v77, v74
	v_rcp_f32_e32 v74, v75
	v_lshlrev_b32_e32 v60, 4, v60
	v_mul_lo_u32 v63, v63, s76
	v_add3_u32 v60, 0, v61, v60
	v_lshlrev_b32_e32 v61, 4, v62
	ds_write_b128 v60, v[4:7] offset:51200
	v_add3_u32 v60, 0, v63, v61
	ds_write_b128 v60, v[8:11] offset:51200
	s_nop 0
	v_lshlrev_b32_e32 v92, 16, v30
	v_mul_f32_e32 v92, 0xbfb8aa3b, v92
	v_exp_f32_e32 v92, v92
	v_and_b32_e32 v93, 0xffff0000, v30
	v_lshlrev_b32_e32 v96, 16, v31
	v_mul_f32_e32 v93, 0xbfb8aa3b, v93
	v_and_b32_e32 v97, 0xffff0000, v31
	v_exp_f32_e32 v93, v93
	v_mul_f32_e32 v96, 0xbfb8aa3b, v96
	v_exp_f32_e32 v96, v96
	v_mul_f32_e32 v97, 0xbfb8aa3b, v97
	v_exp_f32_e32 v97, v97
	v_ashrrev_i32_e32 v105, 7, v2
	v_add_f32_e32 v98, 1.0, v96
	s_nop 0
	v_pk_add_f32 v[66:67], v[56:57], 1.0 op_sel_hi:[1,0] neg_lo:[1,0] neg_hi:[1,0]
	v_pk_add_f32 v[64:65], v[58:59], 1.0 op_sel_hi:[1,0] neg_lo:[1,0] neg_hi:[1,0]
	v_fma_f32 v75, v78, v66, v56
	v_fma_f32 v83, v79, v67, v57
	v_log_f32_e32 v84, v75
	v_log_f32_e32 v85, v83
	v_rcp_f32_e32 v75, v82
	v_add_f32_e32 v82, 1.0, v80
	v_add_f32_e32 v83, 1.0, v81
	v_rcp_f32_e32 v82, v82
	v_rcp_f32_e32 v83, v83
	s_nop 0
	v_pk_add_f32 v[62:63], v[52:53], 1.0 op_sel_hi:[1,0] neg_lo:[1,0] neg_hi:[1,0]
	v_pk_add_f32 v[60:61], v[54:55], 1.0 op_sel_hi:[1,0] neg_lo:[1,0] neg_hi:[1,0]
	v_fma_f32 v86, v76, v64, v58
	v_fma_f32 v87, v77, v65, v59
	v_fma_f32 v88, v74, v62, v52
	v_log_f32_e32 v86, v86
	v_log_f32_e32 v87, v87
	v_fma_f32 v89, v75, v63, v53
	v_fma_f32 v90, v82, v60, v54
	v_fma_f32 v91, v83, v61, v55
	v_log_f32_e32 v88, v88
	v_log_f32_e32 v89, v89
	v_log_f32_e32 v90, v90
	v_log_f32_e32 v91, v91
	v_pk_mul_f32 v[84:85], v[84:85], s[66:67] op_sel_hi:[1,0]
	v_pk_mul_f32 v[86:87], v[86:87], s[66:67] op_sel_hi:[1,0]
	ds_write_b128 v104, v[84:87]
	v_pk_mul_f32 v[84:85], v[88:89], s[66:67] op_sel_hi:[1,0]
	v_pk_mul_f32 v[86:87], v[90:91], s[66:67] op_sel_hi:[1,0]
	ds_write_b128 v104, v[84:87] offset:16
	v_lshlrev_b32_e32 v84, 16, v28
	v_and_b32_e32 v85, 0xffff0000, v28
	v_mul_f32_e32 v84, 0xbfb8aa3b, v84
	v_exp_f32_e32 v84, v84
	v_mul_f32_e32 v85, 0xbfb8aa3b, v85
	v_exp_f32_e32 v85, v85
	v_lshlrev_b32_e32 v88, 16, v29
	v_add_f32_e32 v86, 1.0, v84
	v_rcp_f32_e32 v86, v86
	v_add_f32_e32 v87, 1.0, v85
	v_rcp_f32_e32 v87, v87
	v_mul_f32_e32 v88, 0xbfb8aa3b, v88
	v_exp_f32_e32 v88, v88
	v_fma_f32 v90, v86, v66, v56
	v_and_b32_e32 v89, 0xffff0000, v29
	v_log_f32_e32 v110, v90
	v_fma_f32 v90, v87, v67, v57
	v_mul_f32_e32 v89, 0xbfb8aa3b, v89
	v_log_f32_e32 v111, v90
	v_add_f32_e32 v90, 1.0, v88
	v_exp_f32_e32 v89, v89
	v_rcp_f32_e32 v90, v90
	v_rcp_f32_e32 v98, v98
	v_add_f32_e32 v99, 1.0, v97
	v_add_f32_e32 v91, 1.0, v89
	v_fma_f32 v94, v90, v64, v58
	v_rcp_f32_e32 v91, v91
	v_log_f32_e32 v112, v94
	v_add_f32_e32 v94, 1.0, v92
	v_rcp_f32_e32 v94, v94
	v_fma_f32 v95, v91, v65, v59
	v_log_f32_e32 v113, v95
	v_rcp_f32_e32 v99, v99
	v_fma_f32 v95, v94, v62, v52
	v_log_f32_e32 v114, v95
	v_add_f32_e32 v95, 1.0, v93
	v_rcp_f32_e32 v95, v95
	v_lshlrev_b32_e32 v101, 13, v105
	v_pk_mul_f32 v[110:111], v[110:111], s[66:67] op_sel_hi:[1,0]
	v_pk_mul_f32 v[112:113], v[112:113], s[66:67] op_sel_hi:[1,0]
	v_fma_f32 v109, v95, v63, v53
	v_log_f32_e32 v115, v109
	v_fma_f32 v109, v98, v60, v54
	v_log_f32_e32 v116, v109
	v_fma_f32 v109, v99, v61, v55
	v_log_f32_e32 v117, v109
	ds_write_b128 v104, v[110:113] offset:16384
	v_pk_mul_f32 v[110:111], v[114:115], s[66:67] op_sel_hi:[1,0]
	v_add_u32_e32 v109, v100, v101
	v_pk_mul_f32 v[112:113], v[116:117], s[66:67] op_sel_hi:[1,0]
	ds_write_b128 v104, v[110:113] offset:16400
	s_waitcnt lgkmcnt(0)
	s_barrier
	ds_read2st64_b32 v[112:113], v109 offset1:2
	ds_read2st64_b32 v[114:115], v109 offset0:4 offset1:6
	ds_read2st64_b32 v[116:117], v109 offset0:8 offset1:10
	ds_read2st64_b32 v[130:131], v109 offset0:12 offset1:14
	ds_read2st64_b32 v[132:133], v109 offset0:16 offset1:18
	ds_read2st64_b32 v[134:135], v109 offset0:20 offset1:22
	ds_read2st64_b32 v[136:137], v109 offset0:24 offset1:26
	ds_read2st64_b32 v[138:139], v109 offset0:28 offset1:30
	s_waitcnt lgkmcnt(7)
	v_add_f32_e32 v128, 0, v112
	v_add_f32_e32 v129, v128, v113
	s_waitcnt lgkmcnt(6)
	v_add_f32_e32 v123, v129, v114
	v_add_f32_e32 v127, v123, v115
	s_waitcnt lgkmcnt(5)
	v_add_f32_e32 v121, v127, v116
	v_add_f32_e32 v122, v121, v117
	s_waitcnt lgkmcnt(4)
	v_add_f32_e32 v119, v122, v130
	v_add_f32_e32 v120, v119, v131
	s_waitcnt lgkmcnt(3)
	v_add_f32_e32 v117, v120, v132
	v_add_f32_e32 v118, v117, v133
	s_waitcnt lgkmcnt(2)
	v_add_f32_e32 v115, v118, v134
	v_add_f32_e32 v116, v115, v135
	s_waitcnt lgkmcnt(1)
	v_add_f32_e32 v113, v116, v136
	v_add_f32_e32 v114, v113, v137
	s_waitcnt lgkmcnt(0)
	v_add_f32_e32 v111, v114, v138
	v_cmp_lt_i32_e32 vcc, 0, v105
	v_mov_b32_e32 v110, 0
	v_add_f32_e32 v112, v111, v139
	ds_write_b32 v103, v112
	s_waitcnt lgkmcnt(0)
	s_barrier
	s_and_saveexec_b64 s[6:7], vcc
	s_cbranch_execnz .LBB0_475
	s_or_b64 exec, exec, s[6:7]
	v_cmp_lt_i32_e64 s[8:9], 1, v105
	s_and_saveexec_b64 s[6:7], s[8:9]
	s_cbranch_execnz .LBB0_476

.LBB0_460:
	s_or_b64 exec, exec, s[10:11]
	v_mul_u32_u24_e32 v2, 0x120, v112
	v_add_u32_e32 v3, v111, v2
	v_add_u32_e32 v2, v110, v2
	s_waitcnt lgkmcnt(0)
	s_barrier
	ds_read_b64_tr_b16 v[54:55], v2 offset:33920
	ds_read_b64_tr_b16 v[52:53], v2 offset:32768
	ds_read_b64_tr_b16 v[58:59], v3 offset:52352
	ds_read_b64_tr_b16 v[56:57], v3 offset:51200
	ds_read_b64_tr_b16 v[62:63], v3 offset:52384
	ds_read_b64_tr_b16 v[60:61], v3 offset:51232
	ds_read_b64_tr_b16 v[66:67], v2 offset:33928
	ds_read_b64_tr_b16 v[64:65], v2 offset:32776
	ds_read_b64_tr_b16 v[74:75], v2 offset:32832
	ds_read_b64_tr_b16 v[78:79], v2 offset:32840
	ds_read_b64_tr_b16 v[76:77], v2 offset:33984
	ds_read_b64_tr_b16 v[80:81], v2 offset:33992
	ds_read_b64_tr_b16 v[94:95], v2 offset:41984
	ds_read_b64_tr_b16 v[96:97], v2 offset:43136
	s_waitcnt lgkmcnt(10)
	v_mfma_f32_16x16x32_bf16 v[82:85], v[52:55], v[56:59], 0
	s_lshl_b64 s[6:7], s[8:9], 21
	s_add_u32 s6, s35, s6
	s_addc_u32 s7, s42, s7
	s_waitcnt lgkmcnt(6)
	v_mfma_f32_16x16x32_bf16 v[86:89], v[64:67], v[56:59], 0
	s_add_u32 s6, s6, s80
	s_addc_u32 s7, s7, 0
	v_mov_b32_e32 v69, v1
	s_waitcnt lgkmcnt(3)
	v_mfma_f32_16x16x32_bf16 v[90:93], v[74:77], v[56:59], 0
	s_cmpk_gt_i32 s78, 0x7ff
	s_waitcnt lgkmcnt(2)
	v_mfma_f32_16x16x32_bf16 v[56:59], v[78:81], v[56:59], 0
	v_mfma_f32_16x16x32_bf16 v[52:55], v[52:55], v[60:63], 0
	v_mfma_f32_16x16x32_bf16 v[64:67], v[64:67], v[60:63], 0
	v_mfma_f32_16x16x32_bf16 v[74:77], v[74:77], v[60:63], 0
	v_mfma_f32_16x16x32_bf16 v[60:63], v[78:81], v[60:63], 0
	ds_read_b64_tr_b16 v[78:79], v3 offset:60416
	ds_read_b64_tr_b16 v[80:81], v3 offset:61568
	ds_read_b64_tr_b16 v[100:101], v3 offset:61600
	ds_read_b64_tr_b16 v[98:99], v3 offset:60448
	ds_read_b64_tr_b16 v[104:105], v2 offset:43144
	ds_read_b64_tr_b16 v[102:103], v2 offset:41992
	ds_read_b64_tr_b16 v[106:107], v2 offset:42048
	ds_read_b64_tr_b16 v[110:111], v2 offset:42056
	ds_read_b64_tr_b16 v[108:109], v2 offset:43200
	ds_read_b64_tr_b16 v[112:113], v2 offset:43208
	v_lshl_add_u64 v[2:3], s[6:7], 0, v[0:1]
	v_lshl_add_u64 v[2:3], v[2:3], 0, v[68:69]
	s_waitcnt lgkmcnt(8)
	v_mfma_f32_16x16x32_bf16 v[82:85], v[94:97], v[78:81], v[82:85]
	s_mov_b64 s[6:7], -1
	s_waitcnt lgkmcnt(4)
	v_mfma_f32_16x16x32_bf16 v[86:89], v[102:105], v[78:81], v[86:89]
	s_waitcnt lgkmcnt(1)
	v_mfma_f32_16x16x32_bf16 v[90:93], v[106:109], v[78:81], v[90:93]
	s_nop 2
	v_cvt_pk_bf16_f32 v68, v82, v83
	v_cvt_pk_bf16_f32 v69, v84, v85
	s_waitcnt lgkmcnt(0)
	v_mfma_f32_16x16x32_bf16 v[56:59], v[110:113], v[78:81], v[56:59]
	v_lshl_add_u64 v[78:79], v[2:3], 0, v[70:71]
	v_cvt_pk_bf16_f32 v70, v86, v87
	v_cvt_pk_bf16_f32 v71, v88, v89
	v_mfma_f32_16x16x32_bf16 v[52:55], v[94:97], v[98:101], v[52:55]
	global_store_dwordx4 v[78:79], v[68:71], off
	v_lshl_add_u64 v[2:3], v[2:3], 0, v[72:73]
	v_mfma_f32_16x16x32_bf16 v[64:67], v[102:105], v[98:101], v[64:67]
	v_mfma_f32_16x16x32_bf16 v[68:71], v[106:109], v[98:101], v[74:77]
	s_nop 3
	v_cvt_pk_bf16_f32 v52, v52, v53
	v_cvt_pk_bf16_f32 v53, v54, v55
	s_nop 0
	v_cvt_pk_bf16_f32 v54, v64, v65
	v_mfma_f32_16x16x32_bf16 v[60:63], v[110:113], v[98:101], v[60:63]
	v_cvt_pk_bf16_f32 v55, v66, v67
	v_cvt_pk_bf16_f32 v74, v90, v91
	v_cvt_pk_bf16_f32 v75, v92, v93
	v_cvt_pk_bf16_f32 v76, v56, v57
	v_cvt_pk_bf16_f32 v77, v58, v59
	global_store_dwordx4 v[2:3], v[52:55], off
	global_store_dwordx4 v[78:79], v[74:77], off offset:64
	s_nop 0
	v_cvt_pk_bf16_f32 v52, v68, v69
	v_cvt_pk_bf16_f32 v53, v70, v71
	v_cvt_pk_bf16_f32 v54, v60, v61
	v_cvt_pk_bf16_f32 v55, v62, v63
	global_store_dwordx4 v[2:3], v[52:55], off offset:64
	s_barrier
	s_cbranch_scc1 .LBB0_445
	s_add_i32 s6, s89, s79
	s_cmpk_gt_i32 s6, 0x7ff
	s_cbranch_scc1 .Llbp_b8
	v_mov_b32_e32 v0, v204
	s_ashr_i32 s6, s6, 8
	v_ashrrev_i32_e32 v2, 31, v0
	v_lshrrev_b32_e32 v2, 28, v2
	v_add_u32_e32 v3, v0, v2
	s_ashr_i32 s7, s6, 31
	s_add_i32 s8, s88, s77
	v_ashrrev_i32_e32 v2, 4, v3
	v_and_b32_e32 v3, 0x1ffffff0, v3
	s_lshl_b64 s[6:7], s[6:7], 12
	s_and_b32 s8, s8, 0xfc0
	v_sub_u32_e32 v3, v0, v3
	s_or_b32 s6, s6, s8
	v_lshlrev_b32_e32 v4, 3, v3
	v_ashrrev_i32_e32 v3, 31, v2
	s_add_i32 s8, s91, s2
	v_lshl_add_u64 v[2:3], s[6:7], 0, v[2:3]
	v_mov_b64_e32 v[24:25], s[54:55]
	s_and_b32 s10, s8, 0x180
	v_mad_u64_u32 v[6:7], s[8:9], v2, s46, v[24:25]
	v_mad_i32_i24 v7, v3, s46, v7
	s_lshl_b32 s26, s10, 1
	v_lshl_add_u64 v[2:3], v[6:7], 0, s[26:27]
	v_ashrrev_i32_e32 v5, 31, v4
	v_lshl_add_u64 v[2:3], v[4:5], 1, v[2:3]
	v_add_u32_e32 v5, 0x200, v0
	v_ashrrev_i32_e32 v4, 31, v5
	v_lshrrev_b32_e32 v4, 28, v4
	v_add_u32_e32 v6, v5, v4
	v_ashrrev_i32_e32 v4, 4, v6
	v_and_b32_e32 v6, 0x1ffffff0, v6
	v_sub_u32_e32 v5, v5, v6
	v_lshlrev_b32_e32 v6, 3, v5
	v_ashrrev_i32_e32 v5, 31, v4
	v_lshl_add_u64 v[4:5], s[6:7], 0, v[4:5]
	v_mad_u64_u32 v[8:9], s[8:9], v4, s46, v[24:25]
	v_mad_i32_i24 v9, v5, s46, v9
	v_add_co_u32_e32 v2, vcc, s1, v2
	v_lshl_add_u64 v[4:5], v[8:9], 0, s[26:27]
	v_ashrrev_i32_e32 v7, 31, v6
	v_addc_co_u32_e32 v3, vcc, 0, v3, vcc
	v_lshl_add_u64 v[4:5], v[6:7], 1, v[4:5]
	v_add_co_u32_e32 v8, vcc, s1, v4
	s_nop 1
	v_addc_co_u32_e32 v9, vcc, 0, v5, vcc
	global_load_dwordx4 v[4:7], v[2:3], off offset:1024
	s_nop 0
	global_load_dwordx4 v[8:11], v[8:9], off offset:1024
	v_ashrrev_i32_e32 v2, 4, v0
	v_ashrrev_i32_e32 v3, 31, v2
	v_lshl_add_u64 v[12:13], s[6:7], 0, v[2:3]
	v_add_u32_e32 v2, 32, v2
	v_ashrrev_i32_e32 v3, 31, v2
	v_lshl_add_u64 v[2:3], s[6:7], 0, v[2:3]
	v_mad_u64_u32 v[14:15], s[8:9], v12, s46, v[24:25]
	v_mad_u64_u32 v[24:25], s[6:7], v2, s46, v[24:25]
	v_mad_i32_i24 v15, v13, s46, v15
	v_lshlrev_b32_e32 v0, 4, v0
	v_mad_i32_i24 v25, v3, s46, v25
	v_lshl_add_u64 v[12:13], v[14:15], 0, s[26:27]
	v_and_b32_e32 v0, 0xf0, v0
	v_lshl_add_u64 v[2:3], v[24:25], 0, s[26:27]
	v_lshl_add_u64 v[12:13], v[12:13], 0, v[0:1]
	v_lshl_add_u64 v[2:3], v[2:3], 0, v[0:1]
	v_lshl_add_u64 v[14:15], v[12:13], 0, s[64:65]
	v_lshl_add_u64 v[24:25], v[2:3], 0, s[64:65]
	global_load_dwordx4 v[16:19], v[12:13], off offset:3072
	s_nop 0
	global_load_dwordx4 v[12:15], v[14:15], off offset:1024
	s_nop 0
	global_load_dwordx4 v[28:31], v[2:3], off offset:3072
	s_nop 0
	global_load_dwordx4 v[24:27], v[24:25], off offset:1024
	s_waitcnt vmcnt(14)
.LBB0_463:
	s_bfe_u32 s26, s78, 0x20006
	v_mov_b32_e32 v2, v204
	s_lshl_b32 s6, s26, 9
	v_lshlrev_b32_e32 v0, 3, v2
	v_and_b32_e32 v107, 0x78, v0
	s_add_u32 s6, s33, s6
	s_addc_u32 s7, s34, 0
	v_lshlrev_b32_e32 v60, 2, v107
	v_mov_b32_e32 v56, v240
	v_mov_b32_e32 v57, v241
	v_mov_b32_e32 v58, v242
	v_mov_b32_e32 v59, v243
	v_mov_b32_e32 v52, v244
	v_mov_b32_e32 v53, v245
	v_mov_b32_e32 v54, v246
	v_mov_b32_e32 v55, v247
	s_add_i32 s100, s78, s22
	s_bfe_u32 s100, s100, 0x20006
	s_lshl_b32 s100, s100, 9
	s_add_u32 s98, s33, s100
	s_addc_u32 s99, s34, 0
	global_load_dwordx4 v[240:243], v60, s[98:99]
	global_load_dwordx4 v[244:247], v60, s[98:99] offset:16
	v_lshlrev_b32_e32 v3, 16, v36
	v_and_b32_e32 v61, 0xffff0000, v36
	v_mul_f32_e32 v66, 0xbfb8aa3b, v3
	v_mul_f32_e32 v61, 0xbfb8aa3b, v61
	v_exp_f32_e32 v72, v66
	v_exp_f32_e32 v73, v61
	v_lshlrev_b32_e32 v62, 16, v37
	v_and_b32_e32 v63, 0xffff0000, v37
	v_lshlrev_b32_e32 v64, 16, v38
	v_and_b32_e32 v65, 0xffff0000, v38
	v_mul_f32_e32 v62, 0xbfb8aa3b, v62
	v_mul_f32_e32 v63, 0xbfb8aa3b, v63
	v_mul_f32_e32 v64, 0xbfb8aa3b, v64
	v_mul_f32_e32 v65, 0xbfb8aa3b, v65
	v_ashrrev_i32_e32 v3, 31, v2
	v_add_u32_e32 v67, 0x200, v2
	v_exp_f32_e32 v70, v62
	v_lshlrev_b32_e32 v80, 16, v39
	v_and_b32_e32 v81, 0xffff0000, v39
	v_lshlrev_b32_e32 v74, 2, v2
	v_exp_f32_e32 v71, v63
	v_exp_f32_e32 v68, v64
	v_exp_f32_e32 v69, v65
	v_lshrrev_b32_e32 v61, 28, v3
	v_ashrrev_i32_e32 v62, 31, v67
	v_add_f32_e32 v64, 1.0, v72
	v_add_f32_e32 v65, 1.0, v73
	v_ashrrev_i32_e32 v108, 4, v2
	v_and_b32_e32 v63, 0x1fc, v74
	v_add_u32_e32 v61, v2, v61
	v_lshrrev_b32_e32 v62, 28, v62
	v_rcp_f32_e32 v78, v64
	v_rcp_f32_e32 v79, v65
	v_mul_f32_e32 v80, 0xbfb8aa3b, v80
	v_mul_f32_e32 v81, 0xbfb8aa3b, v81
	v_lshlrev_b32_e32 v106, 9, v108
	v_add_u32_e32 v100, 0, v63
	v_add_u32_e32 v102, s92, v63
	v_lshrrev_b32_e32 v63, 4, v61
	v_and_b32_e32 v61, 0xffffff0, v61
	v_add_u32_e32 v62, v67, v62
	v_exp_f32_e32 v80, v80
	v_exp_f32_e32 v81, v81
	v_add3_u32 v104, 0, v106, v60
	v_sub_u32_e32 v60, v2, v61
	v_mul_lo_u32 v61, v63, s76
	v_lshrrev_b32_e32 v63, 4, v62
	v_and_b32_e32 v62, 0xffffff0, v62
	v_add_f32_e32 v66, 1.0, v70
	v_add_u32_e32 v103, s92, v74
	v_add_f32_e32 v74, 1.0, v71
	v_add_f32_e32 v75, 1.0, v68
	v_sub_u32_e32 v62, v67, v62
	v_rcp_f32_e32 v76, v66
	v_add_f32_e32 v82, 1.0, v69
	v_rcp_f32_e32 v77, v74
	v_rcp_f32_e32 v74, v75
	v_lshlrev_b32_e32 v60, 4, v60
	v_mul_lo_u32 v63, v63, s76
	v_add3_u32 v60, 0, v61, v60
	v_lshlrev_b32_e32 v61, 4, v62
	ds_write_b128 v60, v[20:23] offset:51200
	v_add3_u32 v60, 0, v63, v61
	ds_write_b128 v60, v[32:35] offset:51200
	v_lshlrev_b32_e32 v92, 16, v46
	v_mul_f32_e32 v92, 0xbfb8aa3b, v92
	v_exp_f32_e32 v92, v92
	v_and_b32_e32 v93, 0xffff0000, v46
	v_lshlrev_b32_e32 v96, 16, v47
	v_mul_f32_e32 v93, 0xbfb8aa3b, v93
	v_and_b32_e32 v97, 0xffff0000, v47
	v_exp_f32_e32 v93, v93
	v_mul_f32_e32 v96, 0xbfb8aa3b, v96
	v_exp_f32_e32 v96, v96
	v_mul_f32_e32 v97, 0xbfb8aa3b, v97
	v_exp_f32_e32 v97, v97
	v_ashrrev_i32_e32 v105, 7, v2
	v_add_f32_e32 v98, 1.0, v96
	s_nop 0
	v_pk_add_f32 v[66:67], v[56:57], 1.0 op_sel_hi:[1,0] neg_lo:[1,0] neg_hi:[1,0]
	v_pk_add_f32 v[64:65], v[58:59], 1.0 op_sel_hi:[1,0] neg_lo:[1,0] neg_hi:[1,0]
	v_fma_f32 v75, v78, v66, v56
	v_fma_f32 v83, v79, v67, v57
	v_log_f32_e32 v84, v75
	v_log_f32_e32 v85, v83
	v_rcp_f32_e32 v75, v82
	v_add_f32_e32 v82, 1.0, v80
	v_add_f32_e32 v83, 1.0, v81
	v_rcp_f32_e32 v82, v82
	v_rcp_f32_e32 v83, v83
	s_nop 0
	v_pk_add_f32 v[62:63], v[52:53], 1.0 op_sel_hi:[1,0] neg_lo:[1,0] neg_hi:[1,0]
	v_pk_add_f32 v[60:61], v[54:55], 1.0 op_sel_hi:[1,0] neg_lo:[1,0] neg_hi:[1,0]
	v_fma_f32 v86, v76, v64, v58
	v_fma_f32 v87, v77, v65, v59
	v_fma_f32 v88, v74, v62, v52
	v_log_f32_e32 v86, v86
	v_log_f32_e32 v87, v87
	v_fma_f32 v89, v75, v63, v53
	v_fma_f32 v90, v82, v60, v54
	v_fma_f32 v91, v83, v61, v55
	v_log_f32_e32 v88, v88
	v_log_f32_e32 v89, v89
	v_log_f32_e32 v90, v90
	v_log_f32_e32 v91, v91
	v_pk_mul_f32 v[84:85], v[84:85], s[66:67] op_sel_hi:[1,0]
	v_pk_mul_f32 v[86:87], v[86:87], s[66:67] op_sel_hi:[1,0]
	ds_write_b128 v104, v[84:87]
	v_pk_mul_f32 v[84:85], v[88:89], s[66:67] op_sel_hi:[1,0]
	v_pk_mul_f32 v[86:87], v[90:91], s[66:67] op_sel_hi:[1,0]
	ds_write_b128 v104, v[84:87] offset:16
	v_lshlrev_b32_e32 v84, 16, v44
	v_and_b32_e32 v85, 0xffff0000, v44
	v_mul_f32_e32 v84, 0xbfb8aa3b, v84
	v_exp_f32_e32 v84, v84
	v_mul_f32_e32 v85, 0xbfb8aa3b, v85
	v_exp_f32_e32 v85, v85
	v_lshlrev_b32_e32 v88, 16, v45
	v_add_f32_e32 v86, 1.0, v84
	v_rcp_f32_e32 v86, v86
	v_add_f32_e32 v87, 1.0, v85
	v_rcp_f32_e32 v87, v87
	v_mul_f32_e32 v88, 0xbfb8aa3b, v88
	v_exp_f32_e32 v88, v88
	v_fma_f32 v90, v86, v66, v56
	v_and_b32_e32 v89, 0xffff0000, v45
	v_log_f32_e32 v110, v90
	v_fma_f32 v90, v87, v67, v57
	v_mul_f32_e32 v89, 0xbfb8aa3b, v89
	v_log_f32_e32 v111, v90
	v_add_f32_e32 v90, 1.0, v88
	v_exp_f32_e32 v89, v89
	v_rcp_f32_e32 v90, v90
	v_rcp_f32_e32 v98, v98
	v_add_f32_e32 v99, 1.0, v97
	v_add_f32_e32 v91, 1.0, v89
	v_fma_f32 v94, v90, v64, v58
	v_rcp_f32_e32 v91, v91
	v_log_f32_e32 v112, v94
	v_add_f32_e32 v94, 1.0, v92
	v_rcp_f32_e32 v94, v94
	v_fma_f32 v95, v91, v65, v59
	v_log_f32_e32 v113, v95
	v_rcp_f32_e32 v99, v99
	v_fma_f32 v95, v94, v62, v52
	v_log_f32_e32 v114, v95
	v_add_f32_e32 v95, 1.0, v93
	v_rcp_f32_e32 v95, v95
	v_lshlrev_b32_e32 v101, 13, v105
	v_pk_mul_f32 v[110:111], v[110:111], s[66:67] op_sel_hi:[1,0]
	v_pk_mul_f32 v[112:113], v[112:113], s[66:67] op_sel_hi:[1,0]
	v_fma_f32 v109, v95, v63, v53
	v_log_f32_e32 v115, v109
	v_fma_f32 v109, v98, v60, v54
	v_log_f32_e32 v116, v109
	v_fma_f32 v109, v99, v61, v55
	v_log_f32_e32 v117, v109
	ds_write_b128 v104, v[110:113] offset:16384
	v_pk_mul_f32 v[110:111], v[114:115], s[66:67] op_sel_hi:[1,0]
	v_add_u32_e32 v109, v100, v101
	v_pk_mul_f32 v[112:113], v[116:117], s[66:67] op_sel_hi:[1,0]
	ds_write_b128 v104, v[110:113] offset:16400
	s_waitcnt lgkmcnt(0)
	s_barrier
	ds_read2st64_b32 v[112:113], v109 offset1:2
	ds_read2st64_b32 v[114:115], v109 offset0:4 offset1:6
	ds_read2st64_b32 v[116:117], v109 offset0:8 offset1:10
	ds_read2st64_b32 v[130:131], v109 offset0:12 offset1:14
	ds_read2st64_b32 v[132:133], v109 offset0:16 offset1:18
	ds_read2st64_b32 v[134:135], v109 offset0:20 offset1:22
	ds_read2st64_b32 v[136:137], v109 offset0:24 offset1:26
	ds_read2st64_b32 v[138:139], v109 offset0:28 offset1:30
	s_waitcnt lgkmcnt(7)
	v_add_f32_e32 v128, 0, v112
	v_add_f32_e32 v129, v128, v113
	s_waitcnt lgkmcnt(6)
	v_add_f32_e32 v123, v129, v114
	v_add_f32_e32 v127, v123, v115
	s_waitcnt lgkmcnt(5)
	v_add_f32_e32 v121, v127, v116
	v_add_f32_e32 v122, v121, v117
	s_waitcnt lgkmcnt(4)
	v_add_f32_e32 v119, v122, v130
	v_add_f32_e32 v120, v119, v131
	s_waitcnt lgkmcnt(3)
	v_add_f32_e32 v117, v120, v132
	v_add_f32_e32 v118, v117, v133
	s_waitcnt lgkmcnt(2)
	v_add_f32_e32 v115, v118, v134
	v_add_f32_e32 v116, v115, v135
	s_waitcnt lgkmcnt(1)
	v_add_f32_e32 v113, v116, v136
	v_add_f32_e32 v114, v113, v137
	s_waitcnt lgkmcnt(0)
	v_add_f32_e32 v111, v114, v138
	v_cmp_lt_i32_e32 vcc, 0, v105
	v_mov_b32_e32 v110, 0
	v_add_f32_e32 v112, v111, v139
	ds_write_b32 v103, v112
	s_waitcnt lgkmcnt(0)
	s_barrier
	s_and_saveexec_b64 s[6:7], vcc
	s_cbranch_execnz .LBB0_479
	s_or_b64 exec, exec, s[6:7]
	v_cmp_lt_i32_e64 s[8:9], 1, v105
	s_and_saveexec_b64 s[6:7], s[8:9]
	s_cbranch_execnz .LBB0_480

.LBB0_782:
	v_mov_b32_e32 v2, v0
	v_mov_b32_e32 v3, v0
	v_mov_b32_e32 v1, v0
	v_mov_b64_e32 v[18:19], v[2:3]
	s_waitcnt vmcnt(0)
	v_mov_b64_e32 v[26:27], v[2:3]
	v_mov_b64_e32 v[38:39], v[2:3]
	v_mov_b64_e32 v[42:43], v[2:3]
	v_mov_b64_e32 v[46:47], v[2:3]
	v_mov_b64_e32 v[50:51], v[2:3]
	v_readlane_b32 s61, v238, 11
	s_mov_b32 s73, s3
	s_mov_b32 s2, s97
	v_mov_b64_e32 v[16:17], v[0:1]
	v_mov_b64_e32 v[24:25], v[0:1]
	v_mov_b64_e32 v[36:37], v[0:1]
	v_mov_b64_e32 v[40:41], v[0:1]
	v_mov_b64_e32 v[44:45], v[0:1]
	v_mov_b64_e32 v[48:49], v[0:1]
	s_bfe_u32 s100, s97, 0x20006
	s_lshl_b32 s100, s100, 9
	s_add_u32 s98, s45, s100
	s_addc_u32 s99, s20, 0
	v_and_b32_e32 v239, 15, v204
	v_lshlrev_b32_e32 v239, 5, v239
	global_load_dwordx4 v[240:243], v239, s[98:99]
	global_load_dwordx4 v[244:247], v239, s[98:99] offset:16
	s_waitcnt vmcnt(0)
	s_branch .LBB0_785

.LBB0_787:
	s_ashr_i32 s6, s2, 8
	s_and_b32 s10, s2, 63
	s_ashr_i32 s7, s6, 31
	s_bfe_u32 s64, s2, 0x20006
	v_mov_b32_e32 v143, v204
	s_lshl_b64 s[84:85], s[6:7], 12
	s_lshl_b32 s7, s10, 6
	s_or_b32 s84, s84, s7
	v_lshlrev_b32_e32 v1, 3, v143
	s_lshl_b32 s62, s64, 8
	s_lshl_b32 s7, s64, 9
	v_and_b32_e32 v133, 0x78, v1
	s_add_u32 s8, s45, s7
	s_addc_u32 s9, s20, 0
	v_lshlrev_b32_e32 v68, 2, v133
	v_mov_b32_e32 v56, v240
	v_mov_b32_e32 v57, v241
	v_mov_b32_e32 v58, v242
	v_mov_b32_e32 v59, v243
	v_mov_b32_e32 v52, v244
	v_mov_b32_e32 v53, v245
	v_mov_b32_e32 v54, v246
	v_mov_b32_e32 v55, v247
	s_add_i32 s100, s2, s22
	s_bfe_u32 s100, s100, 0x20006
	s_lshl_b32 s100, s100, 9
	s_add_u32 s98, s45, s100
	s_addc_u32 s99, s20, 0
	global_load_dwordx4 v[240:243], v68, s[98:99]
	global_load_dwordx4 v[244:247], v68, s[98:99] offset:16
	v_ashrrev_i32_e32 v110, 4, v143
	v_ashrrev_i32_e32 v60, 31, v143
	v_add_u32_e32 v69, 0x200, v143
	v_ashrrev_i32_e32 v111, 31, v110
	v_mov_b64_e32 v[2:3], s[66:67]
	v_lshrrev_b32_e32 v64, 28, v60
	v_ashrrev_i32_e32 v65, 31, v69
	v_lshl_add_u64 v[62:63], s[84:85], 0, v[110:111]
	v_lshlrev_b32_e32 v61, 2, v143
	v_add_u32_e32 v112, 32, v110
	v_add_u32_e32 v70, v143, v64
	v_lshrrev_b32_e32 v71, 28, v65
	v_mad_u64_u32 v[64:65], s[8:9], v62, s0, v[2:3]
	v_and_b32_e32 v66, 0x1fc, v61
	v_ashrrev_i32_e32 v113, 31, v112
	s_lshl_b32 s8, s6, 3
	s_lshl_b32 s9, s64, 1
	v_add_u32_e32 v142, 0, v66
	v_add_u32_e32 v147, s92, v66
	v_lshl_add_u64 v[66:67], s[84:85], 0, v[112:113]
	s_or_b32 s86, s9, s8
	v_mad_u64_u32 v[2:3], s[6:7], v66, s0, v[2:3]
	s_ashr_i32 s87, s86, 31
	v_ashrrev_i32_e32 v132, 2, v143
	v_lshrrev_b32_e32 v62, 4, v70
	v_and_b32_e32 v70, 0xffffff0, v70
	s_add_i32 s51, 0, 0x17000
	s_lshl_b64 s[6:7], s[86:87], 21
	v_bfi_b32 v60, -16, v132, v143
	v_lshlrev_b32_e32 v134, 9, v110
	v_add_u32_e32 v71, v69, v71
	v_mad_i32_i24 v65, v63, s0, v65
	v_sub_u32_e32 v63, v143, v70
	s_add_u32 s6, s21, s6
	v_add_u32_e32 v149, s92, v61
	v_ashrrev_i32_e32 v61, 31, v60
	v_add3_u32 v150, 0, v134, v68
	v_mul_lo_u32 v62, v62, s34
	v_and_b32_e32 v68, 0xffffff0, v71
	v_lshlrev_b32_e32 v63, 4, v63
	s_addc_u32 s7, s33, s7
	s_lshl_b32 s8, s10, 15
	v_mov_b32_e32 v93, v0
	v_lshlrev_b32_e32 v92, 1, v133
	v_lshlrev_b64 v[102:103], 8, v[60:61]
	v_lshrrev_b32_e32 v66, 4, v71
	v_lshl_add_u64 v[60:61], v[64:65], 0, s[62:63]
	v_mad_i32_i24 v3, v67, s0, v3
	v_sub_u32_e32 v64, v69, v68
	v_add3_u32 v62, s51, v62, v63
	s_add_u32 s6, s6, s8
	v_lshlrev_b32_e32 v84, 16, v12
	v_mul_lo_u32 v65, v66, s34
	v_lshl_add_u64 v[60:61], v[60:61], 0, v[92:93]
	v_lshl_add_u64 v[2:3], v[2:3], 0, s[62:63]
	v_lshlrev_b32_e32 v63, 4, v64
	ds_write_b128 v62, v[4:7]
	s_addc_u32 s7, s7, 0
	v_and_b32_e32 v85, 0xffff0000, v12
	v_mul_f32_e32 v84, 0xbfb8aa3b, v84
	v_lshl_add_u64 v[2:3], v[2:3], 0, v[92:93]
	v_add3_u32 v62, s51, v65, v63
	global_load_dwordx4 v[80:83], v[60:61], off offset:2048
	global_load_dwordx4 v[76:79], v[2:3], off offset:2048
	v_lshl_add_u64 v[60:61], s[6:7], 0, v[102:103]
	v_and_b32_e32 v118, 48, v143
	v_mov_b32_e32 v119, v0
	v_exp_f32_e32 v84, v84
	v_mul_f32_e32 v85, 0xbfb8aa3b, v85
	ds_write_b128 v62, v[8:11]
	v_lshl_add_u64 v[60:61], v[60:61], 0, v[118:119]
	v_exp_f32_e32 v85, v85
	global_load_dwordx4 v[72:75], v[60:61], off
	global_load_dwordx4 v[68:71], v[60:61], off offset:64
	global_load_dwordx4 v[64:67], v[60:61], off offset:128
	s_nop 0
	global_load_dwordx4 v[60:63], v[60:61], off offset:192
	v_add_f32_e32 v86, 1.0, v84
	v_lshlrev_b32_e32 v88, 16, v13
	v_rcp_f32_e32 v86, v86
	v_add_f32_e32 v87, 1.0, v85
	v_and_b32_e32 v89, 0xffff0000, v13
	v_rcp_f32_e32 v87, v87
	v_mul_f32_e32 v88, 0xbfb8aa3b, v88
	v_lshlrev_b32_e32 v93, 16, v14
	v_exp_f32_e32 v88, v88
	v_mul_f32_e32 v89, 0xbfb8aa3b, v89
	s_nop 0
	v_pk_add_f32 v[98:99], v[56:57], 1.0 op_sel_hi:[1,0] neg_lo:[1,0] neg_hi:[1,0]
	v_exp_f32_e32 v89, v89
	v_mul_f32_e32 v93, 0xbfb8aa3b, v93
	v_fma_f32 v90, v86, v98, v56
	v_exp_f32_e32 v100, v93
	v_log_f32_e32 v108, v90
	v_fma_f32 v90, v87, v99, v57
	v_log_f32_e32 v109, v90
	v_add_f32_e32 v90, 1.0, v88
	v_rcp_f32_e32 v90, v90
	v_add_f32_e32 v91, 1.0, v89
	v_and_b32_e32 v101, 0xffff0000, v14
	v_rcp_f32_e32 v91, v91
	v_add_f32_e32 v104, 1.0, v100
	v_rcp_f32_e32 v104, v104
	v_mul_f32_e32 v101, 0xbfb8aa3b, v101
	v_pk_add_f32 v[96:97], v[58:59], 1.0 op_sel_hi:[1,0] neg_lo:[1,0] neg_hi:[1,0]
	v_exp_f32_e32 v101, v101
	v_fma_f32 v93, v90, v96, v58
	s_nop 0
	v_pk_add_f32 v[94:95], v[52:53], 1.0 op_sel_hi:[1,0] neg_lo:[1,0] neg_hi:[1,0]
	v_log_f32_e32 v116, v93
	v_fma_f32 v93, v91, v97, v59
	v_log_f32_e32 v117, v93
	v_fma_f32 v93, v104, v94, v52
	v_lshlrev_b32_e32 v106, 16, v15
	v_log_f32_e32 v120, v93
	v_add_f32_e32 v93, 1.0, v101
	v_and_b32_e32 v107, 0xffff0000, v15
	v_rcp_f32_e32 v105, v93
	v_mul_f32_e32 v93, 0xbfb8aa3b, v106
	v_exp_f32_e32 v106, v93
	v_mul_f32_e32 v93, 0xbfb8aa3b, v107
	v_exp_f32_e32 v107, v93
	v_pk_add_f32 v[2:3], v[54:55], 1.0 op_sel_hi:[1,0] neg_lo:[1,0] neg_hi:[1,0]
	v_add_f32_e32 v111, 1.0, v106
	v_rcp_f32_e32 v122, v111
	v_add_f32_e32 v111, 1.0, v107
	v_rcp_f32_e32 v123, v111
	v_fma_f32 v93, v105, v95, v53
	v_log_f32_e32 v121, v93
	v_fma_f32 v93, v122, v2, v54
	v_log_f32_e32 v124, v93
	v_fma_f32 v93, v123, v3, v55
	v_log_f32_e32 v125, v93
	v_lshlrev_b32_e32 v93, 16, v20
	v_pk_mul_f32 v[114:115], v[108:109], s[78:79] op_sel_hi:[1,0]
	v_pk_mul_f32 v[116:117], v[116:117], s[78:79] op_sel_hi:[1,0]
	v_and_b32_e32 v108, 0xffff0000, v20
	v_mul_f32_e32 v93, 0xbfb8aa3b, v93
	ds_write_b128 v150, v[114:117]
	v_pk_mul_f32 v[116:117], v[124:125], s[78:79] op_sel_hi:[1,0]
	v_exp_f32_e32 v124, v93
	v_mul_f32_e32 v93, 0xbfb8aa3b, v108
	v_exp_f32_e32 v125, v93
	v_lshlrev_b32_e32 v109, 16, v21
	v_add_f32_e32 v108, 1.0, v124
	v_rcp_f32_e32 v128, v108
	v_add_f32_e32 v108, 1.0, v125
	v_and_b32_e32 v111, 0xffff0000, v21
	v_rcp_f32_e32 v129, v108
	v_mul_f32_e32 v109, 0xbfb8aa3b, v109
	v_lshlrev_b32_e32 v113, 16, v22
	v_exp_f32_e32 v130, v109
	v_mul_f32_e32 v109, 0xbfb8aa3b, v111
	v_exp_f32_e32 v131, v109
	v_mul_f32_e32 v111, 0xbfb8aa3b, v113
	v_fma_f32 v108, v128, v98, v56
	v_exp_f32_e32 v126, v111
	v_log_f32_e32 v136, v108
	v_fma_f32 v108, v129, v99, v57
	v_log_f32_e32 v137, v108
	v_add_f32_e32 v108, 1.0, v130
	v_pk_mul_f32 v[114:115], v[120:121], s[78:79] op_sel_hi:[1,0]
	v_rcp_f32_e32 v108, v108
	v_add_f32_e32 v109, 1.0, v131
	ds_write_b128 v150, v[114:117] offset:16
	v_and_b32_e32 v115, 0xffff0000, v22
	v_rcp_f32_e32 v109, v109
	v_add_f32_e32 v113, 1.0, v126
	v_lshlrev_b32_e32 v93, 16, v23
	v_rcp_f32_e32 v114, v113
	v_mul_f32_e32 v113, 0xbfb8aa3b, v115
	v_and_b32_e32 v117, 0xffff0000, v23
	v_exp_f32_e32 v127, v113
	v_mul_f32_e32 v93, 0xbfb8aa3b, v93
	v_fma_f32 v111, v108, v96, v58
	v_exp_f32_e32 v116, v93
	v_mul_f32_e32 v93, 0xbfb8aa3b, v117
	v_log_f32_e32 v138, v111
	v_fma_f32 v111, v109, v97, v59
	v_exp_f32_e32 v117, v93
	v_log_f32_e32 v139, v111
	v_fma_f32 v111, v114, v94, v52
	v_log_f32_e32 v140, v111
	v_add_f32_e32 v111, 1.0, v127
	v_rcp_f32_e32 v115, v111
	v_add_f32_e32 v111, 1.0, v116
	v_rcp_f32_e32 v120, v111
	v_add_f32_e32 v111, 1.0, v117
	v_rcp_f32_e32 v121, v111
	v_fma_f32 v93, v115, v95, v53
	v_log_f32_e32 v141, v93
	v_fma_f32 v93, v120, v2, v54
	v_log_f32_e32 v144, v93
	v_fma_f32 v93, v121, v3, v55
	v_log_f32_e32 v145, v93
	v_ashrrev_i32_e32 v1, 7, v143
	v_lshlrev_b32_e32 v146, 13, v1
	v_pk_mul_f32 v[136:137], v[136:137], s[78:79] op_sel_hi:[1,0]
	v_pk_mul_f32 v[138:139], v[138:139], s[78:79] op_sel_hi:[1,0]
	ds_write_b128 v150, v[136:139] offset:16384
	v_pk_mul_f32 v[136:137], v[140:141], s[78:79] op_sel_hi:[1,0]
	v_pk_mul_f32 v[138:139], v[144:145], s[78:79] op_sel_hi:[1,0]
	v_add_u32_e32 v111, v142, v146
	ds_write_b128 v150, v[136:139] offset:16400
	s_waitcnt lgkmcnt(0)
	s_barrier
	ds_read2st64_b32 v[136:137], v111 offset1:2
	ds_read2st64_b32 v[138:139], v111 offset0:4 offset1:6
	ds_read2st64_b32 v[140:141], v111 offset0:8 offset1:10
	ds_read2st64_b32 v[144:145], v111 offset0:12 offset1:14
	ds_read2st64_b32 v[160:161], v111 offset0:16 offset1:18
	ds_read2st64_b32 v[162:163], v111 offset0:20 offset1:22
	ds_read2st64_b32 v[164:165], v111 offset0:24 offset1:26
	ds_read2st64_b32 v[166:167], v111 offset0:28 offset1:30
	s_waitcnt lgkmcnt(7)
	v_add_f32_e32 v158, 0, v136
	v_add_f32_e32 v159, v158, v137
	s_waitcnt lgkmcnt(6)
	v_add_f32_e32 v156, v159, v138
	v_add_f32_e32 v157, v156, v139
	s_waitcnt lgkmcnt(5)
	v_add_f32_e32 v154, v157, v140
	v_add_f32_e32 v155, v154, v141
	s_waitcnt lgkmcnt(4)
	v_add_f32_e32 v152, v155, v144
	v_add_f32_e32 v153, v152, v145
	s_waitcnt lgkmcnt(3)
	v_add_f32_e32 v141, v153, v160
	v_add_f32_e32 v145, v141, v161
	s_waitcnt lgkmcnt(2)
	v_add_f32_e32 v139, v145, v162
	v_add_f32_e32 v140, v139, v163
	s_waitcnt lgkmcnt(1)
	v_add_f32_e32 v137, v140, v164
	v_add_f32_e32 v138, v137, v165
	s_waitcnt lgkmcnt(0)
	v_add_f32_e32 v135, v138, v166
	v_cmp_lt_i32_e32 vcc, 0, v1
	v_mov_b32_e32 v113, 0
	v_add_f32_e32 v136, v135, v167
	ds_write_b32 v149, v136
	s_waitcnt lgkmcnt(0)
	s_barrier
	s_and_saveexec_b64 s[6:7], vcc
	s_cbranch_execz .LBB0_789
	ds_read_b32 v93, v147
	s_waitcnt lgkmcnt(0)
	v_add_f32_e32 v113, 0, v93

.LBB0_808:
	s_ashr_i32 s6, s50, 8
	s_and_b32 s10, s50, 63
	s_ashr_i32 s7, s6, 31
	s_bfe_u32 s2, s50, 0x20006
	v_mov_b32_e32 v143, v204
	s_lshl_b64 s[84:85], s[6:7], 12
	s_lshl_b32 s7, s10, 6
	s_or_b32 s84, s84, s7
	v_lshlrev_b32_e32 v2, 3, v143
	s_lshl_b32 s62, s2, 8
	s_lshl_b32 s7, s2, 9
	v_and_b32_e32 v133, 0x78, v2
	s_add_u32 s8, s45, s7
	s_addc_u32 s9, s20, 0
	v_lshlrev_b32_e32 v68, 2, v133
	v_mov_b32_e32 v56, v240
	v_mov_b32_e32 v57, v241
	v_mov_b32_e32 v58, v242
	v_mov_b32_e32 v59, v243
	v_mov_b32_e32 v52, v244
	v_mov_b32_e32 v53, v245
	v_mov_b32_e32 v54, v246
	v_mov_b32_e32 v55, v247
	s_add_i32 s100, s50, s22
	s_bfe_u32 s100, s100, 0x20006
	s_lshl_b32 s100, s100, 9
	s_add_u32 s98, s45, s100
	s_addc_u32 s99, s20, 0
	global_load_dwordx4 v[240:243], v68, s[98:99]
	global_load_dwordx4 v[244:247], v68, s[98:99] offset:16
	v_ashrrev_i32_e32 v110, 4, v143
	v_ashrrev_i32_e32 v60, 31, v143
	v_add_u32_e32 v69, 0x200, v143
	v_ashrrev_i32_e32 v111, 31, v110
	v_mov_b64_e32 v[2:3], s[66:67]
	v_lshrrev_b32_e32 v64, 28, v60
	v_ashrrev_i32_e32 v65, 31, v69
	v_lshl_add_u64 v[62:63], s[84:85], 0, v[110:111]
	v_lshlrev_b32_e32 v61, 2, v143
	v_add_u32_e32 v112, 32, v110
	v_add_u32_e32 v70, v143, v64
	v_lshrrev_b32_e32 v71, 28, v65
	v_mad_u64_u32 v[64:65], s[8:9], v62, s0, v[2:3]
	v_and_b32_e32 v66, 0x1fc, v61
	v_ashrrev_i32_e32 v113, 31, v112
	s_lshl_b32 s8, s6, 3
	s_lshl_b32 s9, s2, 1
	v_add_u32_e32 v145, 0, v66
	v_add_u32_e32 v147, s92, v66
	v_lshl_add_u64 v[66:67], s[84:85], 0, v[112:113]
	s_or_b32 s86, s9, s8
	v_mad_u64_u32 v[2:3], s[6:7], v66, s0, v[2:3]
	s_ashr_i32 s87, s86, 31
	v_ashrrev_i32_e32 v132, 2, v143
	v_lshrrev_b32_e32 v62, 4, v70
	v_and_b32_e32 v70, 0xffffff0, v70
	s_lshl_b64 s[6:7], s[86:87], 21
	v_bfi_b32 v60, -16, v132, v143
	v_lshlrev_b32_e32 v135, 9, v110
	v_add_u32_e32 v71, v69, v71
	v_mad_i32_i24 v65, v63, s0, v65
	v_sub_u32_e32 v63, v143, v70
	s_add_u32 s6, s21, s6
	v_add_u32_e32 v149, s92, v61
	v_ashrrev_i32_e32 v61, 31, v60
	v_add3_u32 v151, 0, v135, v68
	v_mul_lo_u32 v62, v62, s34
	v_and_b32_e32 v68, 0xffffff0, v71
	v_lshlrev_b32_e32 v63, 4, v63
	s_addc_u32 s7, s33, s7
	s_lshl_b32 s8, s10, 15
	v_mov_b32_e32 v95, v0
	v_lshlrev_b32_e32 v94, 1, v133
	v_lshlrev_b64 v[102:103], 8, v[60:61]
	v_lshrrev_b32_e32 v66, 4, v71
	v_lshl_add_u64 v[60:61], v[64:65], 0, s[62:63]
	v_mad_i32_i24 v3, v67, s0, v3
	v_sub_u32_e32 v64, v69, v68
	v_add3_u32 v62, s51, v62, v63
	s_add_u32 s6, s6, s8
	v_lshlrev_b32_e32 v84, 16, v36
	v_mul_lo_u32 v65, v66, s34
	v_lshl_add_u64 v[60:61], v[60:61], 0, v[94:95]
	v_lshl_add_u64 v[2:3], v[2:3], 0, s[62:63]
	v_lshlrev_b32_e32 v63, 4, v64
	ds_write_b128 v62, v[16:19]
	s_addc_u32 s7, s7, 0
	v_and_b32_e32 v85, 0xffff0000, v36
	v_mul_f32_e32 v84, 0xbfb8aa3b, v84
	v_lshl_add_u64 v[2:3], v[2:3], 0, v[94:95]
	v_add3_u32 v62, s51, v65, v63
	global_load_dwordx4 v[80:83], v[60:61], off offset:2048
	global_load_dwordx4 v[76:79], v[2:3], off offset:2048
	v_lshl_add_u64 v[60:61], s[6:7], 0, v[102:103]
	v_and_b32_e32 v118, 48, v143
	v_mov_b32_e32 v119, v0
	v_exp_f32_e32 v84, v84
	v_mul_f32_e32 v85, 0xbfb8aa3b, v85
	ds_write_b128 v62, v[24:27]
	v_lshl_add_u64 v[60:61], v[60:61], 0, v[118:119]
	v_exp_f32_e32 v85, v85
	global_load_dwordx4 v[72:75], v[60:61], off
	global_load_dwordx4 v[68:71], v[60:61], off offset:64
	global_load_dwordx4 v[64:67], v[60:61], off offset:128
	s_nop 0
	global_load_dwordx4 v[60:63], v[60:61], off offset:192
	v_add_f32_e32 v86, 1.0, v84
	v_lshlrev_b32_e32 v88, 16, v37
	v_rcp_f32_e32 v86, v86
	v_add_f32_e32 v87, 1.0, v85
	v_and_b32_e32 v89, 0xffff0000, v37
	v_rcp_f32_e32 v87, v87
	v_mul_f32_e32 v88, 0xbfb8aa3b, v88
	v_lshlrev_b32_e32 v95, 16, v38
	v_exp_f32_e32 v88, v88
	v_mul_f32_e32 v89, 0xbfb8aa3b, v89
	s_nop 0
	v_pk_add_f32 v[98:99], v[56:57], 1.0 op_sel_hi:[1,0] neg_lo:[1,0] neg_hi:[1,0]
	v_exp_f32_e32 v89, v89
	v_mul_f32_e32 v95, 0xbfb8aa3b, v95
	v_fma_f32 v90, v86, v98, v56
	v_exp_f32_e32 v100, v95
	v_log_f32_e32 v108, v90
	v_fma_f32 v90, v87, v99, v57
	v_log_f32_e32 v109, v90
	v_add_f32_e32 v90, 1.0, v88
	v_rcp_f32_e32 v90, v90
	v_add_f32_e32 v91, 1.0, v89
	v_and_b32_e32 v101, 0xffff0000, v38
	v_rcp_f32_e32 v91, v91
	v_add_f32_e32 v104, 1.0, v100
	v_rcp_f32_e32 v104, v104
	v_mul_f32_e32 v101, 0xbfb8aa3b, v101
	v_pk_add_f32 v[96:97], v[58:59], 1.0 op_sel_hi:[1,0] neg_lo:[1,0] neg_hi:[1,0]
	v_exp_f32_e32 v101, v101
	v_fma_f32 v95, v90, v96, v58
	s_nop 0
	v_pk_add_f32 v[92:93], v[52:53], 1.0 op_sel_hi:[1,0] neg_lo:[1,0] neg_hi:[1,0]
	v_log_f32_e32 v116, v95
	v_fma_f32 v95, v91, v97, v59
	v_log_f32_e32 v117, v95
	v_fma_f32 v95, v104, v92, v52
	v_lshlrev_b32_e32 v106, 16, v39
	v_log_f32_e32 v120, v95
	v_add_f32_e32 v95, 1.0, v101
	v_and_b32_e32 v107, 0xffff0000, v39
	v_rcp_f32_e32 v105, v95
	v_mul_f32_e32 v95, 0xbfb8aa3b, v106
	v_exp_f32_e32 v106, v95
	v_mul_f32_e32 v95, 0xbfb8aa3b, v107
	v_exp_f32_e32 v107, v95
	v_pk_add_f32 v[2:3], v[54:55], 1.0 op_sel_hi:[1,0] neg_lo:[1,0] neg_hi:[1,0]
	v_add_f32_e32 v111, 1.0, v106
	v_rcp_f32_e32 v122, v111
	v_add_f32_e32 v111, 1.0, v107
	v_rcp_f32_e32 v123, v111
	v_fma_f32 v95, v105, v93, v53
	v_log_f32_e32 v121, v95
	v_fma_f32 v95, v122, v2, v54
	v_log_f32_e32 v124, v95
	v_fma_f32 v95, v123, v3, v55
	v_log_f32_e32 v125, v95
	v_lshlrev_b32_e32 v95, 16, v40
	v_pk_mul_f32 v[114:115], v[108:109], s[78:79] op_sel_hi:[1,0]
	v_pk_mul_f32 v[116:117], v[116:117], s[78:79] op_sel_hi:[1,0]
	v_and_b32_e32 v108, 0xffff0000, v40
	v_mul_f32_e32 v95, 0xbfb8aa3b, v95
	ds_write_b128 v151, v[114:117]
	v_pk_mul_f32 v[116:117], v[124:125], s[78:79] op_sel_hi:[1,0]
	v_exp_f32_e32 v124, v95
	v_mul_f32_e32 v95, 0xbfb8aa3b, v108
	v_exp_f32_e32 v125, v95
	v_lshlrev_b32_e32 v109, 16, v41
	v_add_f32_e32 v108, 1.0, v124
	v_rcp_f32_e32 v128, v108
	v_add_f32_e32 v108, 1.0, v125
	v_and_b32_e32 v111, 0xffff0000, v41
	v_rcp_f32_e32 v129, v108
	v_mul_f32_e32 v109, 0xbfb8aa3b, v109
	v_lshlrev_b32_e32 v113, 16, v42
	v_exp_f32_e32 v130, v109
	v_mul_f32_e32 v109, 0xbfb8aa3b, v111
	v_exp_f32_e32 v131, v109
	v_mul_f32_e32 v111, 0xbfb8aa3b, v113
	v_fma_f32 v108, v128, v98, v56
	v_exp_f32_e32 v126, v111
	v_log_f32_e32 v136, v108
	v_fma_f32 v108, v129, v99, v57
	v_log_f32_e32 v137, v108
	v_add_f32_e32 v108, 1.0, v130
	v_pk_mul_f32 v[114:115], v[120:121], s[78:79] op_sel_hi:[1,0]
	v_rcp_f32_e32 v108, v108
	v_add_f32_e32 v109, 1.0, v131
	ds_write_b128 v151, v[114:117] offset:16
	v_and_b32_e32 v115, 0xffff0000, v42
	v_rcp_f32_e32 v109, v109
	v_add_f32_e32 v113, 1.0, v126
	v_lshlrev_b32_e32 v95, 16, v43
	v_rcp_f32_e32 v114, v113
	v_mul_f32_e32 v113, 0xbfb8aa3b, v115
	v_and_b32_e32 v117, 0xffff0000, v43
	v_exp_f32_e32 v127, v113
	v_mul_f32_e32 v95, 0xbfb8aa3b, v95
	v_fma_f32 v111, v108, v96, v58
	v_exp_f32_e32 v116, v95
	v_mul_f32_e32 v95, 0xbfb8aa3b, v117
	v_log_f32_e32 v138, v111
	v_fma_f32 v111, v109, v97, v59
	v_exp_f32_e32 v117, v95
	v_log_f32_e32 v139, v111
	v_fma_f32 v111, v114, v92, v52
	v_log_f32_e32 v140, v111
	v_add_f32_e32 v111, 1.0, v127
	v_rcp_f32_e32 v115, v111
	v_add_f32_e32 v111, 1.0, v116
	v_rcp_f32_e32 v120, v111
	v_add_f32_e32 v111, 1.0, v117
	v_rcp_f32_e32 v121, v111
	v_fma_f32 v95, v115, v93, v53
	v_log_f32_e32 v141, v95
	v_fma_f32 v95, v120, v2, v54
	v_log_f32_e32 v152, v95
	v_fma_f32 v95, v121, v3, v55
	v_log_f32_e32 v153, v95
	v_ashrrev_i32_e32 v134, 7, v143
	v_lshlrev_b32_e32 v146, 13, v134
	v_pk_mul_f32 v[136:137], v[136:137], s[78:79] op_sel_hi:[1,0]
	v_pk_mul_f32 v[138:139], v[138:139], s[78:79] op_sel_hi:[1,0]
	ds_write_b128 v151, v[136:139] offset:16384
	v_pk_mul_f32 v[136:137], v[140:141], s[78:79] op_sel_hi:[1,0]
	v_pk_mul_f32 v[138:139], v[152:153], s[78:79] op_sel_hi:[1,0]
	v_add_u32_e32 v111, v145, v146
	ds_write_b128 v151, v[136:139] offset:16400
	s_waitcnt lgkmcnt(0)
	s_barrier
	ds_read2st64_b32 v[136:137], v111 offset1:2
	ds_read2st64_b32 v[138:139], v111 offset0:4 offset1:6
	ds_read2st64_b32 v[140:141], v111 offset0:8 offset1:10
	ds_read2st64_b32 v[152:153], v111 offset0:12 offset1:14
	ds_read2st64_b32 v[162:163], v111 offset0:16 offset1:18
	ds_read2st64_b32 v[164:165], v111 offset0:20 offset1:22
	ds_read2st64_b32 v[166:167], v111 offset0:24 offset1:26
	ds_read2st64_b32 v[168:169], v111 offset0:28 offset1:30
	s_waitcnt lgkmcnt(7)
	v_add_f32_e32 v160, 0, v136
	v_add_f32_e32 v161, v160, v137
	s_waitcnt lgkmcnt(6)
	v_add_f32_e32 v158, v161, v138
	v_add_f32_e32 v159, v158, v139
	s_waitcnt lgkmcnt(5)
	v_add_f32_e32 v156, v159, v140
	v_add_f32_e32 v157, v156, v141
	s_waitcnt lgkmcnt(4)
	v_add_f32_e32 v154, v157, v152
	v_add_f32_e32 v155, v154, v153
	s_waitcnt lgkmcnt(3)
	v_add_f32_e32 v150, v155, v162
	v_add_f32_e32 v152, v150, v163
	s_waitcnt lgkmcnt(2)
	v_add_f32_e32 v140, v152, v164
	v_add_f32_e32 v141, v140, v165
	s_waitcnt lgkmcnt(1)
	v_add_f32_e32 v138, v141, v166
	v_add_f32_e32 v139, v138, v167
	s_waitcnt lgkmcnt(0)
	v_add_f32_e32 v136, v139, v168
	v_cmp_lt_i32_e32 vcc, 0, v134
	v_mov_b32_e32 v113, 0
	v_add_f32_e32 v137, v136, v169
	ds_write_b32 v149, v137
	s_waitcnt lgkmcnt(0)
	s_barrier
	s_and_saveexec_b64 s[6:7], vcc
	s_cbranch_execz .LBB0_810
	ds_read_b32 v95, v147
	s_waitcnt lgkmcnt(0)
	v_add_f32_e32 v113, 0, v95
